# hot-loop entry alignment: the 7 GEMM K-loop headers and the attention loop headers aligned to 64-byte instruction-fetch lines with .p2align 6
# baseline (speedup 1.0000x reference)
; template <class Epi, class Sched>
; DI void gemm_phase(LAS unsigned char* lds, const Gemm g, const Sched& S, const Epi& E) {
;     ...
;     const bool has_next = S.next(ui + 1, nxt);
;     const char* nA = has_next ? (const char*)g.A + (size_t)nxt.pm * tstep : cA; const char* nB = has_next ? (const char*)g.Bt + (size_t)nxt.pn * tstep : cB;
; #pragma unroll 1
;     for (int t = 0; t < nt; t += 2) {
;       const bool last = (t == nt - 2);
;       const char* a1 = cA + (size_t)(t + 1) * kstep;
;       const char* a2 = last ? nA : cA + (size_t)(t + 2) * kstep; const char* b2 = last ? nB : cB + (size_t)(t + 2) * kstep;
;       const char* a3 = a2 + kstep; const char* b3 = b2 + kstep;
;     ...
; #pragma unroll
;     for (int a = 0; a < 2; ++a)
; #pragma unroll
;       for (int b = 0; b < 2; ++b)
; #pragma unroll
;         for (int m = 0; m < 4; ++m)
; #pragma unroll
;           for (int n = 0; n < 2; ++n) acc[a][b][m][n] = (f32x4){0.f, 0.f, 0.f, 0.f};
.LBB0_369:
	v_readlane_b32 s18, v239, 44
	v_readlane_b32 s19, v239, 45
	s_ashr_i32 s15, s14, 31
	s_mov_b32 s50, -2
	v_mov_b64_e32 v[0:1], s[18:19]
	v_cmp_lt_i64_e32 vcc, s[16:17], v[0:1]
	s_lshl_b64 s[16:17], s[14:15], 19
	s_add_u32 s16, s35, s16
	s_addc_u32 s17, s38, s17
	s_and_b64 s[18:19], vcc, exec
	s_cselect_b32 s15, s17, s3
	s_cselect_b32 s29, s16, s2
	s_ashr_i32 s13, s12, 31
	s_lshl_b64 s[18:19], s[12:13], 19
	s_add_u32 s18, s24, s18
	s_addc_u32 s19, s39, s19
	s_and_b64 s[20:21], vcc, exec
	s_cselect_b32 s13, s19, s5
	s_cselect_b32 s36, s18, s4
	s_add_u32 s2, s2, 0x40080
	s_addc_u32 s3, s3, 0
	s_add_u32 s37, s4, 0x100
	v_mov_b32_e32 v0, 0
	s_addc_u32 s49, s5, 0
	v_mov_b32_e32 v1, v0
	v_mov_b64_e32 v[2:3], v[0:1]
	v_mov_b64_e32 v[4:5], v[0:1]
	v_mov_b64_e32 v[6:7], v[0:1]
	v_mov_b64_e32 v[8:9], v[0:1]
	v_mov_b64_e32 v[10:11], v[0:1]
	v_mov_b64_e32 v[12:13], v[0:1]
	v_mov_b64_e32 v[14:15], v[0:1]
	v_mov_b64_e32 v[16:17], v[0:1]
	v_mov_b64_e32 v[18:19], v[0:1]
	v_mov_b64_e32 v[20:21], v[0:1]
	v_mov_b64_e32 v[22:23], v[0:1]
	v_mov_b64_e32 v[24:25], v[0:1]
	v_mov_b64_e32 v[26:27], v[0:1]
	v_mov_b64_e32 v[28:29], v[0:1]
	v_mov_b64_e32 v[30:31], v[0:1]
	v_mov_b64_e32 v[32:33], v[0:1]
	v_mov_b64_e32 v[34:35], v[0:1]
	v_mov_b64_e32 v[36:37], v[0:1]
	v_mov_b64_e32 v[38:39], v[0:1]
	v_mov_b64_e32 v[40:41], v[0:1]
	v_mov_b64_e32 v[42:43], v[0:1]
	v_mov_b64_e32 v[44:45], v[0:1]
	v_mov_b64_e32 v[46:47], v[0:1]
	v_mov_b64_e32 v[48:49], v[0:1]
	v_mov_b64_e32 v[50:51], v[0:1]
	v_mov_b64_e32 v[52:53], v[0:1]
	v_mov_b64_e32 v[54:55], v[0:1]
	v_mov_b64_e32 v[56:57], v[0:1]
	v_mov_b64_e32 v[58:59], v[0:1]
	v_mov_b64_e32 v[60:61], v[0:1]
	v_mov_b64_e32 v[62:63], v[0:1]
	v_mov_b64_e32 v[64:65], v[0:1]
	v_mov_b64_e32 v[66:67], v[0:1]
	v_mov_b64_e32 v[68:69], v[0:1]
	v_mov_b64_e32 v[70:71], v[0:1]
	v_mov_b64_e32 v[72:73], v[0:1]
	v_mov_b64_e32 v[74:75], v[0:1]
	v_mov_b64_e32 v[76:77], v[0:1]
	v_mov_b64_e32 v[78:79], v[0:1]
	v_mov_b64_e32 v[80:81], v[0:1]
	v_mov_b64_e32 v[82:83], v[0:1]
	v_mov_b64_e32 v[84:85], v[0:1]
	v_mov_b64_e32 v[86:87], v[0:1]
	v_mov_b64_e32 v[88:89], v[0:1]
	v_mov_b64_e32 v[90:91], v[0:1]
	v_mov_b64_e32 v[92:93], v[0:1]
	v_mov_b64_e32 v[94:95], v[0:1]
	v_mov_b64_e32 v[96:97], v[0:1]
	v_mov_b64_e32 v[98:99], v[0:1]
	v_mov_b64_e32 v[100:101], v[0:1]
	v_mov_b64_e32 v[102:103], v[0:1]
	v_mov_b64_e32 v[104:105], v[0:1]
	v_mov_b64_e32 v[106:107], v[0:1]
	v_mov_b64_e32 v[108:109], v[0:1]
	v_mov_b64_e32 v[110:111], v[0:1]
	v_mov_b64_e32 v[112:113], v[0:1]
	v_mov_b64_e32 v[114:115], v[0:1]
	v_mov_b64_e32 v[116:117], v[0:1]
	v_mov_b64_e32 v[118:119], v[0:1]
	v_mov_b64_e32 v[120:121], v[0:1]
	v_mov_b64_e32 v[122:123], v[0:1]
	v_mov_b64_e32 v[124:125], v[0:1]
	v_mov_b64_e32 v[126:127], v[0:1]
	v_add_u32_e32 v228, 0x10000, v155
	v_add_u32_e32 v229, 0x14000, v155
	v_add_u32_e32 v230, 0x18000, v155
	v_add_u32_e32 v231, 0x1c000, v155
	.p2align	6

; DI void attn_diff_unit(const Params& p, int li, int b, int h, int qb, char* smem, bool pre, int nh, bool has_next) {
;     ...
;   __syncthreads();
;   const float* t5t = (const float*)(p.ws + TB_T5) + h * 512;
;   if (tid < 512) tab[tid] = t5t[tid];
;   const float cL = t5t[0], cR = t5t[510];
;   bf16x8 qf[4];
; #pragma unroll
;   for (int s = 0; s < 4; ++s) qf[s] = *(const bf16x8*)(qd + (size_t)qrow * 1024 + h * 128 + map * 64 + s * 16 + hh * 8);
;   f32x16 O[4];
; #pragma unroll
;   for (int j = 0; j < 4; ++j)
; #pragma unroll
;     for (int i = 0; i < 16; ++i) O[j][i] = 0.f;
;   float m = 0.f, l = 0.f;
;   const int krow = tid >> 4, kpart = tid & 15;
;   const u16* gk = kd + (size_t)(b * S_ + krow) * 1024 + h * 128 + kpart * 8;
;   const u16* gv = vT + (size_t)(b * S_ + krow) * 1024 + h * 128 + kpart * 8;
;   u32x4 rk[4], rv[4];
;   if (!pre) {
; #pragma unroll
;     for (int i = 0; i < 4; ++i) { rk[i] = *(const u32x4*)(gk + (size_t)i * 32 * 1024); rv[i] = *(const u32x4*)(gv + (size_t)i * 32 * 1024); }
;   }
;   auto put_stage = [&](char* kb) {
;     char* vb = kb + 128 * KR;
; #pragma unroll
;     for (int i = 0; i < 4; ++i) {
;       *(u32x4*)(kb + (krow + 32 * i) * KR + kpart * 16) = rk[i];
;       *(u32x4*)(vb + (krow + 32 * i) * VR + kpart * 16) = rv[i];
;     }
;   };
;   auto get_stage = [&](int st) {
;     const int k0 = st * 128;
; #pragma unroll
;     for (int i = 0; i < 4; ++i) { rk[i] = *(const u32x4*)(gk + (size_t)(k0 + i * 32) * 1024); rv[i] = *(const u32x4*)(gv + (size_t)(k0 + i * 32) * 1024); }
;   };
;   if (!pre) put_stage(smem);
;   __syncthreads();
;   get_stage(1);
;   for (int kt = 0; kt < 32; ++kt) {
.LBB0_567:
	s_waitcnt vmcnt(6)
	ds_write_b32 v255, v254
	v_bfe_u32 v4, v146, 2, 2
	v_lshrrev_b32_e32 v5, 3, v146
	v_and_or_b32 v4, v5, 4, v4
	s_mov_b32 s3, 0x40000
	v_mul_u32_u24_e32 v163, 0x140, v4
	v_add_co_u32_e32 v4, vcc, s3, v148
	s_waitcnt lgkmcnt(0)
	s_nop 0
	v_addc_co_u32_e32 v5, vcc, 0, v149, vcc
	v_add_co_u32_e32 v6, vcc, s3, v150
	s_mov_b32 s3, 0x50000
	s_nop 0
	v_addc_co_u32_e32 v7, vcc, 0, v151, vcc
	s_barrier
	global_load_dwordx4 v[116:119], v[4:5], off
	global_load_dwordx4 v[128:131], v[6:7], off
	v_add_co_u32_e32 v4, vcc, s3, v148
	s_and_b32 s35, s39, 0xf80
	s_nop 0
	v_addc_co_u32_e32 v5, vcc, 0, v149, vcc
	v_add_co_u32_e32 v6, vcc, s3, v150
	s_mov_b32 s3, 0x60000
	s_nop 0
	v_addc_co_u32_e32 v7, vcc, 0, v151, vcc
	global_load_dwordx4 v[112:115], v[4:5], off
	global_load_dwordx4 v[120:123], v[6:7], off
	v_add_co_u32_e32 v4, vcc, s3, v148
	s_add_i32 s40, s40, s89
	s_nop 0
	v_addc_co_u32_e32 v5, vcc, 0, v149, vcc
	v_add_co_u32_e32 v6, vcc, s3, v150
	s_mov_b32 s3, 0x70000
	s_nop 0
	v_addc_co_u32_e32 v7, vcc, 0, v151, vcc
	global_load_dwordx4 v[124:127], v[4:5], off
	global_load_dwordx4 v[132:135], v[6:7], off
	v_add_co_u32_e32 v4, vcc, s3, v148
	s_sub_i32 s42, 0, s35
	s_nop 0
	v_addc_co_u32_e32 v5, vcc, 0, v149, vcc
	v_add_co_u32_e32 v6, vcc, s3, v150
	s_lshr_b32 s2, s40, 5
	s_nop 0
	v_addc_co_u32_e32 v7, vcc, 0, v151, vcc
	global_load_dwordx4 v[136:139], v[4:5], off
	global_load_dwordx4 v[140:143], v[6:7], off
	v_and_b32_e32 v158, 63, v146
	s_cmpk_lt_u32 s40, 0x100
	v_lshlrev_b32_e32 v144, 10, v3
	s_cselect_b64 s[28:29], -1, 0
	s_cmpk_gt_u32 s40, 0xff
	v_and_b32_e32 v3, 16, v146
	v_lshlrev_b32_e32 v162, 2, v158
	s_cselect_b64 s[22:23], -1, 0
	v_and_or_b32 v3, v162, 12, v3
	s_sub_i32 s2, s2, s34
	v_lshlrev_b32_e32 v164, 1, v3
	v_lshlrev_b32_e32 v3, 7, v155
	v_add_u32_e32 v166, 0, v160
	s_lshl_b32 s2, s2, 7
	v_or_b32_e32 v1, s35, v1
	v_lshl_or_b32 v165, v2, 4, v3
	v_lshlrev_b32_e32 v153, 2, v2
	v_add_u32_e32 v2, 0, v161
	v_add_u32_e32 v3, 0x8800, v166
	s_ashr_i32 s3, s2, 31
	v_mul_u32_u24_e32 v167, 0x110, v0
	v_add_u32_e32 v0, v1, v0
	v_mov_b32_e32 v169, 0
	s_mov_b32 s24, 0
	v_xor_b32_e32 v147, 0x80, v162
	v_sub_u32_e32 v168, v153, v0
	s_mov_b64 s[34:35], 0xb0000
	v_add_u32_e32 v170, v2, v159
	v_add_u32_e32 v171, v3, v159
	s_lshl_b64 s[36:37], s[2:3], 1
	s_mov_b32 s43, 0
	v_mov_b32_e32 v172, 0
	v_mov_b32_e32 v0, 0
	v_mov_b32_e32 v1, v169
	v_mov_b32_e32 v2, v169
	v_mov_b32_e32 v3, v169
	v_mov_b32_e32 v4, v169
	v_mov_b32_e32 v5, v169
	v_mov_b32_e32 v6, v169
	v_mov_b32_e32 v7, v169
	v_mov_b32_e32 v8, v169
	v_mov_b32_e32 v9, v169
	v_mov_b32_e32 v10, v169
	v_mov_b32_e32 v11, v169
	v_mov_b32_e32 v12, v169
	v_mov_b32_e32 v13, v169
	v_mov_b32_e32 v14, v169
	v_mov_b32_e32 v15, v169
	v_mov_b32_e32 v16, 0
	v_mov_b32_e32 v17, v169
	v_mov_b32_e32 v18, v169
	v_mov_b32_e32 v19, v169
	v_mov_b32_e32 v20, v169
	v_mov_b32_e32 v21, v169
	v_mov_b32_e32 v22, v169
	v_mov_b32_e32 v23, v169
	v_mov_b32_e32 v24, v169
	v_mov_b32_e32 v25, v169
	v_mov_b32_e32 v26, v169
	v_mov_b32_e32 v27, v169
	v_mov_b32_e32 v28, v169
	v_mov_b32_e32 v29, v169
	v_mov_b32_e32 v30, v169
	v_mov_b32_e32 v31, v169
	v_mov_b32_e32 v32, 0
	v_mov_b32_e32 v33, v169
	v_mov_b32_e32 v34, v169
	v_mov_b32_e32 v35, v169
	v_mov_b32_e32 v36, v169
	v_mov_b32_e32 v37, v169
	v_mov_b32_e32 v38, v169
	v_mov_b32_e32 v39, v169
	v_mov_b32_e32 v40, v169
	v_mov_b32_e32 v41, v169
	v_mov_b32_e32 v42, v169
	v_mov_b32_e32 v43, v169
	v_mov_b32_e32 v44, v169
	v_mov_b32_e32 v45, v169
	v_mov_b32_e32 v46, v169
	v_mov_b32_e32 v47, v169
	v_mov_b32_e32 v48, 0
	v_mov_b32_e32 v49, v169
	v_mov_b32_e32 v50, v169
	v_mov_b32_e32 v51, v169
	v_mov_b32_e32 v52, v169
	v_mov_b32_e32 v53, v169
	v_mov_b32_e32 v54, v169
	v_mov_b32_e32 v55, v169
	v_mov_b32_e32 v56, v169
	v_mov_b32_e32 v57, v169
	v_mov_b32_e32 v58, v169
	v_mov_b32_e32 v59, v169
	v_mov_b32_e32 v60, v169
	v_mov_b32_e32 v61, v169
	v_mov_b32_e32 v62, v169
	s_waitcnt vmcnt(8)
	s_mov_b32 s45, 0
	v_readfirstlane_b32 s100, v148
	s_nop 3
	v_subrev_u32_e32 v246, s100, v148
	v_add_u32_e32 v247, 0x10000, v246
	v_add_u32_e32 v248, 0x20000, v246
	v_add_u32_e32 v249, 0x30000, v246
	v_mov_b32_e32 v63, v169
	.p2align	6

; template <class Epi, class Sched>
; DI void gemm_phase(LAS unsigned char* lds, const Gemm g, const Sched& S, const Epi& E) {
;     ...
;     const bool has_next = S.next(ui + 1, nxt);
;     const char* nA = has_next ? (const char*)g.A + (size_t)nxt.pm * tstep : cA; const char* nB = has_next ? (const char*)g.Bt + (size_t)nxt.pn * tstep : cB;
; #pragma unroll 1
;     for (int t = 0; t < nt; t += 2) {
;       const bool last = (t == nt - 2);
;       const char* a1 = cA + (size_t)(t + 1) * kstep;
;       const char* a2 = last ? nA : cA + (size_t)(t + 2) * kstep; const char* b2 = last ? nB : cB + (size_t)(t + 2) * kstep;
;       const char* a3 = a2 + kstep; const char* b3 = b2 + kstep;
;     ...
; #pragma unroll
;     for (int a = 0; a < 2; ++a)
; #pragma unroll
;       for (int b = 0; b < 2; ++b)
; #pragma unroll
;         for (int m = 0; m < 4; ++m)
; #pragma unroll
;           for (int n = 0; n < 2; ++n) acc[a][b][m][n] = (f32x4){0.f, 0.f, 0.f, 0.f};
.LBB0_688:
	v_readlane_b32 s18, v238, 51
	v_readlane_b32 s19, v238, 52
	s_ashr_i32 s13, s12, 31
	s_mov_b32 s41, -2
	v_mov_b64_e32 v[0:1], s[18:19]
	v_cmp_lt_i64_e32 vcc, s[16:17], v[0:1]
	s_lshl_b64 s[16:17], s[12:13], 19
	s_add_u32 s16, s53, s16
	s_addc_u32 s17, s54, s17
	s_and_b64 s[18:19], vcc, exec
	s_cselect_b32 s13, s17, s21
	s_cselect_b32 s37, s16, s20
	s_ashr_i32 s15, s14, 31
	s_lshl_b64 s[18:19], s[14:15], 19
	s_add_u32 s18, s24, s18
	s_addc_u32 s19, s55, s19
	s_and_b64 s[28:29], vcc, exec
	s_cselect_b32 s15, s19, s23
	s_cselect_b32 s38, s18, s22
	s_add_u32 s20, s20, 0x40080
	s_addc_u32 s21, s21, 0
	s_add_u32 s39, s22, 0x100
	v_mov_b32_e32 v0, 0
	s_addc_u32 s40, s23, 0
	v_mov_b32_e32 v1, v0
	v_mov_b64_e32 v[2:3], v[0:1]
	v_mov_b64_e32 v[4:5], v[0:1]
	v_mov_b64_e32 v[6:7], v[0:1]
	v_mov_b64_e32 v[8:9], v[0:1]
	v_mov_b64_e32 v[10:11], v[0:1]
	v_mov_b64_e32 v[12:13], v[0:1]
	v_mov_b64_e32 v[14:15], v[0:1]
	v_mov_b64_e32 v[16:17], v[0:1]
	v_mov_b64_e32 v[18:19], v[0:1]
	v_mov_b64_e32 v[20:21], v[0:1]
	v_mov_b64_e32 v[22:23], v[0:1]
	v_mov_b64_e32 v[24:25], v[0:1]
	v_mov_b64_e32 v[26:27], v[0:1]
	v_mov_b64_e32 v[28:29], v[0:1]
	v_mov_b64_e32 v[30:31], v[0:1]
	v_mov_b64_e32 v[32:33], v[0:1]
	v_mov_b64_e32 v[34:35], v[0:1]
	v_mov_b64_e32 v[36:37], v[0:1]
	v_mov_b64_e32 v[38:39], v[0:1]
	v_mov_b64_e32 v[40:41], v[0:1]
	v_mov_b64_e32 v[42:43], v[0:1]
	v_mov_b64_e32 v[44:45], v[0:1]
	v_mov_b64_e32 v[46:47], v[0:1]
	v_mov_b64_e32 v[48:49], v[0:1]
	v_mov_b64_e32 v[50:51], v[0:1]
	v_mov_b64_e32 v[52:53], v[0:1]
	v_mov_b64_e32 v[54:55], v[0:1]
	v_mov_b64_e32 v[56:57], v[0:1]
	v_mov_b64_e32 v[58:59], v[0:1]
	v_mov_b64_e32 v[60:61], v[0:1]
	v_mov_b64_e32 v[62:63], v[0:1]
	v_mov_b64_e32 v[64:65], v[0:1]
	v_mov_b64_e32 v[66:67], v[0:1]
	v_mov_b64_e32 v[68:69], v[0:1]
	v_mov_b64_e32 v[70:71], v[0:1]
	v_mov_b64_e32 v[72:73], v[0:1]
	v_mov_b64_e32 v[74:75], v[0:1]
	v_mov_b64_e32 v[76:77], v[0:1]
	v_mov_b64_e32 v[78:79], v[0:1]
	v_mov_b64_e32 v[80:81], v[0:1]
	v_mov_b64_e32 v[82:83], v[0:1]
	v_mov_b64_e32 v[84:85], v[0:1]
	v_mov_b64_e32 v[86:87], v[0:1]
	v_mov_b64_e32 v[88:89], v[0:1]
	v_mov_b64_e32 v[90:91], v[0:1]
	v_mov_b64_e32 v[92:93], v[0:1]
	v_mov_b64_e32 v[94:95], v[0:1]
	v_mov_b64_e32 v[96:97], v[0:1]
	v_mov_b64_e32 v[98:99], v[0:1]
	v_mov_b64_e32 v[100:101], v[0:1]
	v_mov_b64_e32 v[102:103], v[0:1]
	v_mov_b64_e32 v[104:105], v[0:1]
	v_mov_b64_e32 v[106:107], v[0:1]
	v_mov_b64_e32 v[108:109], v[0:1]
	v_mov_b64_e32 v[110:111], v[0:1]
	v_mov_b64_e32 v[112:113], v[0:1]
	v_mov_b64_e32 v[114:115], v[0:1]
	v_mov_b64_e32 v[116:117], v[0:1]
	v_mov_b64_e32 v[118:119], v[0:1]
	v_mov_b64_e32 v[120:121], v[0:1]
	v_mov_b64_e32 v[122:123], v[0:1]
	v_mov_b64_e32 v[124:125], v[0:1]
	v_mov_b64_e32 v[126:127], v[0:1]
	v_add_u32_e32 v222, 0x10000, v196
	v_add_u32_e32 v223, 0x14000, v196
	v_add_u32_e32 v224, 0x18000, v196
	v_add_u32_e32 v225, 0x1c000, v196
	.p2align	6

; template <class Epi, class Sched>
; DI void gemm_phase(LAS unsigned char* lds, const Gemm g, const Sched& S, const Epi& E) {
;     ...
;     const bool has_next = S.next(ui + 1, nxt);
;     const char* nA = has_next ? (const char*)g.A + (size_t)nxt.pm * tstep : cA; const char* nB = has_next ? (const char*)g.Bt + (size_t)nxt.pn * tstep : cB;
; #pragma unroll 1
;     for (int t = 0; t < nt; t += 2) {
;       const bool last = (t == nt - 2);
;       const char* a1 = cA + (size_t)(t + 1) * kstep;
;       const char* a2 = last ? nA : cA + (size_t)(t + 2) * kstep; const char* b2 = last ? nB : cB + (size_t)(t + 2) * kstep;
;       const char* a3 = a2 + kstep; const char* b3 = b2 + kstep;
;     ...
; #pragma unroll
;     for (int a = 0; a < 2; ++a)
; #pragma unroll
;       for (int b = 0; b < 2; ++b)
; #pragma unroll
;         for (int m = 0; m < 4; ++m)
; #pragma unroll
;           for (int n = 0; n < 2; ++n) acc[a][b][m][n] = (f32x4){0.f, 0.f, 0.f, 0.f};
.LBB0_1201:
	s_add_u32 s52, s20, 0x100
	v_mov_b32_e32 v0, 0
	s_addc_u32 s53, s21, 0
	s_mov_b32 s54, -2
	v_mov_b32_e32 v1, v0
	v_mov_b64_e32 v[2:3], v[0:1]
	v_mov_b64_e32 v[4:5], v[0:1]
	v_mov_b64_e32 v[6:7], v[0:1]
	v_mov_b64_e32 v[8:9], v[0:1]
	v_mov_b64_e32 v[10:11], v[0:1]
	v_mov_b64_e32 v[12:13], v[0:1]
	v_mov_b64_e32 v[14:15], v[0:1]
	v_mov_b64_e32 v[16:17], v[0:1]
	v_mov_b64_e32 v[18:19], v[0:1]
	v_mov_b64_e32 v[20:21], v[0:1]
	v_mov_b64_e32 v[22:23], v[0:1]
	v_mov_b64_e32 v[24:25], v[0:1]
	v_mov_b64_e32 v[26:27], v[0:1]
	v_mov_b64_e32 v[28:29], v[0:1]
	v_mov_b64_e32 v[30:31], v[0:1]
	v_mov_b64_e32 v[32:33], v[0:1]
	v_mov_b64_e32 v[34:35], v[0:1]
	v_mov_b64_e32 v[36:37], v[0:1]
	v_mov_b64_e32 v[38:39], v[0:1]
	v_mov_b64_e32 v[40:41], v[0:1]
	v_mov_b64_e32 v[42:43], v[0:1]
	v_mov_b64_e32 v[44:45], v[0:1]
	v_mov_b64_e32 v[46:47], v[0:1]
	v_mov_b64_e32 v[48:49], v[0:1]
	v_mov_b64_e32 v[50:51], v[0:1]
	v_mov_b64_e32 v[52:53], v[0:1]
	v_mov_b64_e32 v[54:55], v[0:1]
	v_mov_b64_e32 v[56:57], v[0:1]
	v_mov_b64_e32 v[58:59], v[0:1]
	v_mov_b64_e32 v[60:61], v[0:1]
	v_mov_b64_e32 v[62:63], v[0:1]
	v_mov_b64_e32 v[64:65], v[0:1]
	v_mov_b64_e32 v[66:67], v[0:1]
	v_mov_b64_e32 v[68:69], v[0:1]
	v_mov_b64_e32 v[70:71], v[0:1]
	v_mov_b64_e32 v[72:73], v[0:1]
	v_mov_b64_e32 v[74:75], v[0:1]
	v_mov_b64_e32 v[76:77], v[0:1]
	v_mov_b64_e32 v[78:79], v[0:1]
	v_mov_b64_e32 v[80:81], v[0:1]
	v_mov_b64_e32 v[82:83], v[0:1]
	v_mov_b64_e32 v[84:85], v[0:1]
	v_mov_b64_e32 v[86:87], v[0:1]
	v_mov_b64_e32 v[88:89], v[0:1]
	v_mov_b64_e32 v[90:91], v[0:1]
	v_mov_b64_e32 v[92:93], v[0:1]
	v_mov_b64_e32 v[94:95], v[0:1]
	v_mov_b64_e32 v[96:97], v[0:1]
	v_mov_b64_e32 v[98:99], v[0:1]
	v_mov_b64_e32 v[100:101], v[0:1]
	v_mov_b64_e32 v[102:103], v[0:1]
	v_mov_b64_e32 v[104:105], v[0:1]
	v_mov_b64_e32 v[106:107], v[0:1]
	v_mov_b64_e32 v[108:109], v[0:1]
	v_mov_b64_e32 v[110:111], v[0:1]
	v_mov_b64_e32 v[112:113], v[0:1]
	v_mov_b64_e32 v[114:115], v[0:1]
	v_mov_b64_e32 v[116:117], v[0:1]
	v_mov_b64_e32 v[118:119], v[0:1]
	v_mov_b64_e32 v[120:121], v[0:1]
	v_mov_b64_e32 v[122:123], v[0:1]
	v_mov_b64_e32 v[124:125], v[0:1]
	v_mov_b64_e32 v[126:127], v[0:1]
	v_add_u32_e32 v224, 0x10000, v162
	v_add_u32_e32 v225, 0x14000, v162
	v_add_u32_e32 v226, 0x18000, v162
	v_add_u32_e32 v227, 0x1c000, v162
	.p2align	6

; template <class Epi, class Sched>
; DI void gemm_phase(LAS unsigned char* lds, const Gemm g, const Sched& S, const Epi& E) {
;     ...
;     const bool has_next = S.next(ui + 1, nxt);
;     const char* nA = has_next ? (const char*)g.A + (size_t)nxt.pm * tstep : cA; const char* nB = has_next ? (const char*)g.Bt + (size_t)nxt.pn * tstep : cB;
; #pragma unroll 1
;     for (int t = 0; t < nt; t += 2) {
;       const bool last = (t == nt - 2);
;       const char* a1 = cA + (size_t)(t + 1) * kstep;
;       const char* a2 = last ? nA : cA + (size_t)(t + 2) * kstep; const char* b2 = last ? nB : cB + (size_t)(t + 2) * kstep;
;       const char* a3 = a2 + kstep; const char* b3 = b2 + kstep;
;     ...
; #pragma unroll
;     for (int a = 0; a < 2; ++a)
; #pragma unroll
;       for (int b = 0; b < 2; ++b)
; #pragma unroll
;         for (int m = 0; m < 4; ++m)
; #pragma unroll
;           for (int n = 0; n < 2; ++n) acc[a][b][m][n] = (f32x4){0.f, 0.f, 0.f, 0.f};
.LBB0_1345:
	v_mov_b64_e32 v[0:1], s[30:31]
	s_ashr_i32 s15, s14, 31
	v_cmp_lt_i64_e32 vcc, s[16:17], v[0:1]
	s_lshl_b64 s[16:17], s[14:15], 17
	s_add_u32 s16, s52, s16
	s_addc_u32 s17, s53, s17
	s_and_b64 s[18:19], vcc, exec
	s_cselect_b32 s15, s17, s29
	s_cselect_b32 s21, s16, s28
	s_ashr_i32 s13, s12, 31
	s_lshl_b64 s[18:19], s[12:13], 17
	s_add_u32 s18, s54, s18
	s_addc_u32 s19, s55, s19
	s_and_b64 s[34:35], vcc, exec
	v_mov_b32_e32 v0, 0
	s_cselect_b32 s13, s19, s23
	s_cselect_b32 s24, s18, s22
	s_mov_b64 s[40:41], 0
	s_mov_b64 s[34:35], -1
	s_mov_b64 s[36:37], 0
	v_mov_b32_e32 v1, v0
	v_mov_b64_e32 v[2:3], v[0:1]
	v_mov_b64_e32 v[4:5], v[0:1]
	v_mov_b64_e32 v[6:7], v[0:1]
	v_mov_b64_e32 v[8:9], v[0:1]
	v_mov_b64_e32 v[10:11], v[0:1]
	v_mov_b64_e32 v[12:13], v[0:1]
	v_mov_b64_e32 v[14:15], v[0:1]
	v_mov_b64_e32 v[16:17], v[0:1]
	v_mov_b64_e32 v[18:19], v[0:1]
	v_mov_b64_e32 v[20:21], v[0:1]
	v_mov_b64_e32 v[22:23], v[0:1]
	v_mov_b64_e32 v[24:25], v[0:1]
	v_mov_b64_e32 v[26:27], v[0:1]
	v_mov_b64_e32 v[28:29], v[0:1]
	v_mov_b64_e32 v[30:31], v[0:1]
	v_mov_b64_e32 v[32:33], v[0:1]
	v_mov_b64_e32 v[34:35], v[0:1]
	v_mov_b64_e32 v[36:37], v[0:1]
	v_mov_b64_e32 v[38:39], v[0:1]
	v_mov_b64_e32 v[40:41], v[0:1]
	v_mov_b64_e32 v[42:43], v[0:1]
	v_mov_b64_e32 v[44:45], v[0:1]
	v_mov_b64_e32 v[46:47], v[0:1]
	v_mov_b64_e32 v[48:49], v[0:1]
	v_mov_b64_e32 v[50:51], v[0:1]
	v_mov_b64_e32 v[52:53], v[0:1]
	v_mov_b64_e32 v[54:55], v[0:1]
	v_mov_b64_e32 v[56:57], v[0:1]
	v_mov_b64_e32 v[58:59], v[0:1]
	v_mov_b64_e32 v[60:61], v[0:1]
	v_mov_b64_e32 v[62:63], v[0:1]
	v_mov_b64_e32 v[64:65], v[0:1]
	v_mov_b64_e32 v[66:67], v[0:1]
	v_mov_b64_e32 v[68:69], v[0:1]
	v_mov_b64_e32 v[70:71], v[0:1]
	v_mov_b64_e32 v[72:73], v[0:1]
	v_mov_b64_e32 v[74:75], v[0:1]
	v_mov_b64_e32 v[76:77], v[0:1]
	v_mov_b64_e32 v[78:79], v[0:1]
	v_mov_b64_e32 v[80:81], v[0:1]
	v_mov_b64_e32 v[82:83], v[0:1]
	v_mov_b64_e32 v[84:85], v[0:1]
	v_mov_b64_e32 v[86:87], v[0:1]
	v_mov_b64_e32 v[88:89], v[0:1]
	v_mov_b64_e32 v[90:91], v[0:1]
	v_mov_b64_e32 v[92:93], v[0:1]
	v_mov_b64_e32 v[94:95], v[0:1]
	v_mov_b64_e32 v[96:97], v[0:1]
	v_mov_b64_e32 v[98:99], v[0:1]
	v_mov_b64_e32 v[100:101], v[0:1]
	v_mov_b64_e32 v[102:103], v[0:1]
	v_mov_b64_e32 v[104:105], v[0:1]
	v_mov_b64_e32 v[106:107], v[0:1]
	v_mov_b64_e32 v[108:109], v[0:1]
	v_mov_b64_e32 v[110:111], v[0:1]
	v_mov_b64_e32 v[112:113], v[0:1]
	v_mov_b64_e32 v[114:115], v[0:1]
	v_mov_b64_e32 v[116:117], v[0:1]
	v_mov_b64_e32 v[118:119], v[0:1]
	v_mov_b64_e32 v[120:121], v[0:1]
	v_mov_b64_e32 v[122:123], v[0:1]
	v_mov_b64_e32 v[124:125], v[0:1]
	v_mov_b64_e32 v[126:127], v[0:1]
	v_add_u32_e32 v220, 0x10000, v142
	v_add_u32_e32 v221, 0x14000, v142
	v_add_u32_e32 v222, 0x18000, v142
	v_add_u32_e32 v223, 0x1c000, v142
	.p2align	6

; DI f32x16 mfma32(bf16x8 a, bf16x8 b, f32x16 c) { return __builtin_amdgcn_mfma_f32_32x32x16_bf16(a, b, c, 0, 0, 0); }
; DI void attn_mla_unit(const Params& p, int b, int h, int qb, char* smem, bool pre, int nh, bool has_next) {
;     ...
;     const char* ks = smem + (kt & 1) * STG; const char* vs = ks + 128 * KR;
; #pragma unroll
;     for (int sub = 0; sub < 2; ++sub) {
;       f32x16 s0, s1;
; #pragma unroll
;       for (int i = 0; i < 16; ++i) { s0[i] = -m; s1[i] = -m; }
;       {
;         bf16x8 kf[12];
; #pragma unroll
;         for (int s = 0; s < 6; ++s) {
;           kf[2 * s] = *(const bf16x8*)(ks + (sub * 64 + r32) * KR + (s * 16 + hh * 8) * 2);
;           kf[2 * s + 1] = *(const bf16x8*)(ks + (sub * 64 + 32 + r32) * KR + (s * 16 + hh * 8) * 2);
;         }
;         __builtin_amdgcn_sched_barrier(0); __builtin_amdgcn_s_setprio(1);
; #pragma unroll
;         for (int s = 0; s < 6; ++s) { s0 = mfma32(kf[2 * s], qf[s], s0); s1 = mfma32(kf[2 * s + 1], qf[s], s1); }
;       __builtin_amdgcn_s_setprio(0);
; }
;       float alpha; bf16x8 pf[4];
;       const bool resc = softmax_tile(s0, s1, m, l, alpha, pf, lane, (kt == 0) && (sub == 0), (sub == 0) && ((kt & 3) == 0));
.LBB0_1481:
	ds_read_b128 v[110:113], v141 offset:13312
	ds_read_b128 v[114:117], v141 offset:13344
	ds_read_b128 v[118:121], v141 offset:19968
	ds_read_b128 v[152:155], v141 offset:20000
	ds_read_b128 v[156:159], v141 offset:13376
	ds_read_b128 v[160:163], v141 offset:13408
	ds_read_b128 v[164:167], v141 offset:20032
	ds_read_b128 v[168:171], v141 offset:20064
	ds_read_b128 v[172:175], v141 offset:13440
	ds_read_b128 v[176:179], v141 offset:13472
	ds_read_b128 v[196:199], v141 offset:20096
	ds_read_b128 v[200:203], v141 offset:20128
	s_add_i32 s34, s34, s44
	s_lshr_b32 s10, s34, 4
	s_sub_i32 s10, s10, s35
	s_lshl_b32 s14, s10, 6
	s_lshl_b32 s9, s35, 6
	v_mul_u32_u24_e32 v149, 0xd0, v33
	s_ashr_i32 s15, s14, 31
	v_add_f32_e32 v33, 0, v35
	v_mul_u32_u24_e32 v148, 0xc0, v34
	v_add_f32_e32 v34, 0, v36
	v_add_f32_e32 v35, v33, v37
	s_cmpk_lt_u32 s34, 0x80
	v_mul_f32_e32 v32, v34, v32
	v_cndmask_b32_e64 v150, v35, v33, s[2:3]
	s_cselect_b64 s[10:11], -1, 0
	s_cmpk_gt_u32 s34, 0x7f
	v_ashrrev_i32_e32 v125, 31, v124
	v_add_u32_e32 v109, 0, v142
	v_add_u32_e32 v122, 0, v143
	v_cndmask_b32_e64 v123, v32, v34, s[2:3]
	s_cselect_b64 s[2:3], -1, 0
	v_xor_b32_e32 v32, 0x80000000, v150
	v_mov_b32_e32 v33, v32
	v_mov_b64_e32 v[220:221], v[32:33]
	v_mov_b64_e32 v[222:223], v[32:33]
	v_mov_b64_e32 v[224:225], v[32:33]
	v_mov_b64_e32 v[226:227], v[32:33]
	v_mov_b64_e32 v[228:229], v[32:33]
	v_mov_b64_e32 v[230:231], v[32:33]
	v_mov_b64_e32 v[232:233], v[32:33]
	v_mov_b64_e32 v[234:235], v[32:33]
	v_mov_b32_e32 v34, v32
	v_mov_b32_e32 v35, v32
	v_mov_b32_e32 v36, v32
	v_mov_b32_e32 v37, v32
	v_mov_b32_e32 v38, v32
	v_mov_b32_e32 v39, v32
	v_mov_b32_e32 v40, v32
	v_mov_b32_e32 v41, v32
	v_mov_b32_e32 v42, v32
	v_mov_b32_e32 v43, v32
	v_mov_b32_e32 v44, v32
	v_mov_b32_e32 v45, v32
	v_mov_b32_e32 v46, v32
	v_mov_b32_e32 v47, v32
	s_setprio 1
	s_waitcnt lgkmcnt(11)
	v_mfma_f32_32x32x16_bf16 v[48:63], v[110:113], v[100:103], v[32:47]
	s_waitcnt lgkmcnt(9)
	v_mfma_f32_32x32x16_bf16 v[32:47], v[118:121], v[100:103], v[32:47]
	v_mfma_f32_32x32x16_bf16 v[48:63], v[114:117], v[96:99], v[48:63]
	s_waitcnt lgkmcnt(8)
	v_mfma_f32_32x32x16_bf16 v[32:47], v[152:155], v[96:99], v[32:47]
	s_waitcnt lgkmcnt(7)
	v_mfma_f32_32x32x16_bf16 v[48:63], v[156:159], v[92:95], v[48:63]
	s_waitcnt lgkmcnt(5)
	v_mfma_f32_32x32x16_bf16 v[32:47], v[164:167], v[92:95], v[32:47]
	v_mfma_f32_32x32x16_bf16 v[48:63], v[160:163], v[88:91], v[48:63]
	s_waitcnt lgkmcnt(4)
	v_mfma_f32_32x32x16_bf16 v[32:47], v[168:171], v[88:91], v[32:47]
	s_waitcnt lgkmcnt(3)
	v_mfma_f32_32x32x16_bf16 v[48:63], v[172:175], v[84:87], v[48:63]
	s_waitcnt lgkmcnt(1)
	v_mfma_f32_32x32x16_bf16 v[32:47], v[196:199], v[84:87], v[32:47]
	v_mfma_f32_32x32x16_bf16 v[48:63], v[176:179], v[80:83], v[48:63]
	s_waitcnt lgkmcnt(0)
; DI f32x16 mfma32(bf16x8 a, bf16x8 b, f32x16 c) { return __builtin_amdgcn_mfma_f32_32x32x16_bf16(a, b, c, 0, 0, 0); }
; DI void attn_mla_unit(const Params& p, int b, int h, int qb, char* smem, bool pre, int nh, bool has_next) {
;     ...
;       float alpha; bf16x8 pf[4];
;       const bool resc = softmax_tile(s0, s1, m, l, alpha, pf, lane, (kt == 0) && (sub == 0), (sub == 0) && ((kt & 3) == 0));
;       {
;         bf16x8 vf[8];
; #pragma unroll
;         for (int s = 0; s < 4; ++s) { vf[2 * s] = ld_vfrag_tr(vs, vbase, VR, sub * 64 + 16 * s, 0); vf[2 * s + 1] = ld_vfrag_tr(vs, vbase, VR, sub * 64 + 16 * s, 32); }
;         __builtin_amdgcn_sched_barrier(0); __builtin_amdgcn_s_setprio(1);
; #pragma unroll
;         for (int s = 0; s < 4; ++s) { O0 = mfma32(vf[2 * s], pf[s], O0); O1 = mfma32(vf[2 * s + 1], pf[s], O1); }
;       __builtin_amdgcn_s_setprio(0);
; }
;       if (resc) { scale16(O0, alpha); scale16(O1, alpha); }
;     }
;     if (kt + 1 < 32) put_stage(smem + ((kt + 1) & 1) * STG);
;     else if (has_next) put_stage(smem);
;     __syncthreads();
;     if (kt + 2 < 32) get_stage(kt + 2);
;     else if (kt == 30 && has_next) { gk += (nh - h) * 64; gv += (nh - h) * 64; get_stage(0); }
	v_mfma_f32_32x32x16_bf16 v[32:47], v[200:203], v[80:83], v[32:47]
	s_setprio 0
	s_nop 8
	v_exp_f32_e32 v48, v48
	v_exp_f32_e32 v49, v49
	v_exp_f32_e32 v50, v50
	v_exp_f32_e32 v51, v51
	v_add_f32_e32 v110, 0, v48
	v_exp_f32_e32 v52, v52
	v_add_f32_e32 v110, v49, v110
	v_exp_f32_e32 v53, v53
	v_add_f32_e32 v110, v50, v110
	v_exp_f32_e32 v54, v54
	v_add_f32_e32 v110, v51, v110
	v_exp_f32_e32 v55, v55
	v_add_f32_e32 v110, v52, v110
	v_exp_f32_e32 v56, v56
	v_add_f32_e32 v110, v53, v110
	v_exp_f32_e32 v57, v57
	v_add_f32_e32 v110, v54, v110
	v_exp_f32_e32 v58, v58
	v_add_f32_e32 v110, v55, v110
	v_exp_f32_e32 v59, v59
	v_add_f32_e32 v110, v56, v110
	v_exp_f32_e32 v60, v60
	v_add_f32_e32 v110, v57, v110
	v_exp_f32_e32 v61, v61
	v_add_f32_e32 v110, v58, v110
	v_exp_f32_e32 v62, v62
	v_add_f32_e32 v110, v59, v110
	v_exp_f32_e32 v63, v63
	v_add_f32_e32 v110, v60, v110
	v_exp_f32_e32 v111, v32
	v_add_f32_e32 v110, v61, v110
	v_add_f32_e32 v110, v62, v110
	v_add_f32_e32 v110, v63, v110
	v_add_f32_e32 v32, v111, v110
	v_exp_f32_e32 v110, v33
	v_exp_f32_e32 v112, v34
	v_exp_f32_e32 v113, v35
	v_exp_f32_e32 v114, v36
	v_add_f32_e32 v32, v110, v32
	v_exp_f32_e32 v115, v37
	v_add_f32_e32 v32, v112, v32
	v_exp_f32_e32 v116, v38
	v_add_f32_e32 v32, v113, v32
	v_exp_f32_e32 v39, v39
	v_add_f32_e32 v32, v114, v32
	v_exp_f32_e32 v33, v40
	v_add_f32_e32 v32, v115, v32
	v_exp_f32_e32 v34, v41
	v_add_f32_e32 v32, v116, v32
	v_exp_f32_e32 v35, v42
	v_add_f32_e32 v32, v39, v32
	v_exp_f32_e32 v36, v43
	v_add_f32_e32 v32, v33, v32
	v_exp_f32_e32 v37, v44
	v_add_f32_e32 v32, v34, v32
	v_exp_f32_e32 v38, v45
	v_add_f32_e32 v32, v35, v32
	v_exp_f32_e32 v40, v46
	v_add_f32_e32 v32, v36, v32
	v_exp_f32_e32 v41, v47
	v_add_f32_e32 v32, v37, v32
	v_add_f32_e32 v32, v38, v32
	v_add_f32_e32 v32, v40, v32
	v_add_f32_e32 v32, v41, v32
	v_add_f32_e32 v153, v123, v32
	v_cvt_pk_bf16_f32 v32, v33, v34
	v_cvt_pk_bf16_f32 v33, v35, v36
	v_cvt_pk_bf16_f32 v34, v37, v38
	v_cvt_pk_bf16_f32 v35, v40, v41
	v_cvt_pk_bf16_f32 v36, v111, v110
	v_cvt_pk_bf16_f32 v37, v112, v113
	v_cvt_pk_bf16_f32 v38, v114, v115
	v_cvt_pk_bf16_f32 v39, v116, v39
	v_cvt_pk_bf16_f32 v40, v56, v57
	v_cvt_pk_bf16_f32 v41, v58, v59
	v_cvt_pk_bf16_f32 v42, v60, v61
	v_cvt_pk_bf16_f32 v43, v62, v63
	v_cvt_pk_bf16_f32 v44, v48, v49
	v_cvt_pk_bf16_f32 v45, v50, v51
	v_cvt_pk_bf16_f32 v46, v52, v53
	v_cvt_pk_bf16_f32 v47, v54, v55
	ds_read_b64_tr_b16 v[48:49], v108 offset:38912
	ds_read_b64_tr_b16 v[50:51], v108 offset:40448
	ds_read_b64_tr_b16 v[52:53], v108 offset:38976
	ds_read_b64_tr_b16 v[54:55], v108 offset:40512
	ds_read_b64_tr_b16 v[56:57], v108 offset:41984
	ds_read_b64_tr_b16 v[58:59], v108 offset:43520
	ds_read_b64_tr_b16 v[60:61], v108 offset:42048
	ds_read_b64_tr_b16 v[62:63], v108 offset:43584
	ds_read_b64_tr_b16 v[110:111], v108 offset:45056
	ds_read_b64_tr_b16 v[112:113], v108 offset:46592
	ds_read_b64_tr_b16 v[114:115], v108 offset:45120
	ds_read_b64_tr_b16 v[116:117], v108 offset:46656
	ds_read_b64_tr_b16 v[118:119], v108 offset:48128
	ds_read_b64_tr_b16 v[120:121], v108 offset:49664
	ds_read_b64_tr_b16 v[154:155], v108 offset:48192
	ds_read_b64_tr_b16 v[156:157], v108 offset:49728
	s_setprio 1
	s_waitcnt lgkmcnt(14)
	v_mfma_f32_32x32x16_bf16 v[16:31], v[48:51], v[44:47], v[16:31]
	s_waitcnt lgkmcnt(12)
	v_mfma_f32_32x32x16_bf16 v[0:15], v[52:55], v[44:47], v[0:15]
	s_waitcnt lgkmcnt(10)
	v_mfma_f32_32x32x16_bf16 v[16:31], v[56:59], v[40:43], v[16:31]
	s_waitcnt lgkmcnt(8)
	v_mfma_f32_32x32x16_bf16 v[0:15], v[60:63], v[40:43], v[0:15]
	s_waitcnt lgkmcnt(6)
	v_mfma_f32_32x32x16_bf16 v[16:31], v[110:113], v[36:39], v[16:31]
	s_waitcnt lgkmcnt(4)
	v_mfma_f32_32x32x16_bf16 v[0:15], v[114:117], v[36:39], v[0:15]
	s_waitcnt lgkmcnt(2)
	v_mfma_f32_32x32x16_bf16 v[16:31], v[118:121], v[32:35], v[16:31]
	s_waitcnt lgkmcnt(0)
	v_mfma_f32_32x32x16_bf16 v[0:15], v[154:157], v[32:35], v[0:15]
	s_setprio 0
	v_add_u32_e32 v151, v109, v138
	v_add3_u32 v32, s48, v139, v138
	s_mov_b32 s12, 0x40000
	s_waitcnt vmcnt(4)
	ds_write_b128 v151, v[64:67] offset:51200
	s_waitcnt vmcnt(3)
	ds_write_b128 v32, v[68:71]
	s_waitcnt vmcnt(2)
	ds_write_b128 v151, v[72:75] offset:64512
	s_waitcnt vmcnt(1)
	ds_write_b128 v32, v[76:79] offset:12288
	v_add_co_u32_e32 v32, vcc, s12, v128
	v_add_u32_e32 v152, v122, v146
	s_nop 0
	v_addc_co_u32_e32 v33, vcc, 0, v129, vcc
	v_add_co_u32_e32 v34, vcc, 0x40000, v130
	s_waitcnt vmcnt(0)
	ds_write_b128 v152, v[104:107] offset:51328
	v_addc_co_u32_e32 v35, vcc, 0, v131, vcc
	s_waitcnt lgkmcnt(0)
	s_barrier
	global_load_dwordx4 v[104:107], v[32:33], off
	global_load_dwordx4 v[108:111], v[34:35], off
	v_add_co_u32_e32 v32, vcc, 0x50000, v128
	v_mov_b32_e32 v135, v145
	s_nop 0
	v_addc_co_u32_e32 v33, vcc, 0, v129, vcc
	v_add_co_u32_e32 v34, vcc, 0x50000, v130
	s_mov_b64 s[12:13], 0x70000
	s_nop 0
	v_addc_co_u32_e32 v35, vcc, 0, v131, vcc
	global_load_dwordx4 v[112:115], v[32:33], off
	global_load_dwordx4 v[116:119], v[34:35], off
	v_add_co_u32_e32 v32, vcc, 0x4000, v126
	s_mov_b32 s18, 2
	s_nop 0
	v_addc_co_u32_e32 v33, vcc, 0, v127, vcc
	global_load_dwordx4 v[120:123], v[32:33], off
	v_lshl_add_u64 v[32:33], v[132:133], 0, v[134:135]
	v_lshl_add_u64 v[64:65], s[28:29], 0, v[32:33]
	s_lshl_b64 s[14:15], s[14:15], 1
	.p2align	6

; DI int get_tid() { int t = threadIdx.x; asm volatile("" : "+v"(t)); return t; }
; DI void attn_na_unit(const Params& p, int li, int b, int r, int hp, char* smem) {
;   const int tid = get_tid() & 255, lane = tid & 63, w = tid >> 6, r32 = lane & 31, hh = lane >> 5;
;   char* big = p.ws + B_BIG;
;   const u16* qna = (const u16*)(big + E_QNA);
;   const u16* kna = (const u16*)(big + E_KNA);
;   const u16* vT = (const u16*)(big + E_VNAT);
;   u16* o = (u16*)(p.ws + B_H);
;   char* ks = smem; char* vs = smem + SM_ATT_V; float* tab = (float*)(smem + SM_ATT_TAB);
;   constexpr int KR = 272, VR = 320;
;   const int vbase = tr_base(lane, VR);
;   const int qbk = w & 1, hs = w >> 1, head = 2 * hp + hs;
; __global__ void __launch_bounds__(512) mega(Params p, int ph_lo, int ph_hi) {
;     ...
;         if (jx < nx) {
;           const int half = get_tid() >> 8;
;           char* sm = smem + half * ATT_HALF;
; #pragma unroll 1
;           for (int u = jx; u < 128; u += nx) attn_mla_unit(q, xcd, u >> 4, u & 15, smem, u != jx, (u + nx) >> 4, u + nx < 128);
; #pragma unroll 1
;           for (int up = jx; up < 128; up += nx) { const int u = 2 * up + half; attn_na_unit(q, li, xcd, u >> 2, u & 3, sm); }
.LBB0_1499:
	v_readlane_b32 s10, v237, 12
	v_readlane_b32 s11, v237, 13
	s_add_u32 s6, s10, 0xcda8100
	s_addc_u32 s7, s11, 0
	v_writelane_b32 v237, s6, 14
	v_readlane_b32 s3, v238, 48
	s_waitcnt vmcnt(9)
	v_ashrrev_i32_e32 v116, 8, v136
	v_writelane_b32 v237, s7, 15
	s_add_u32 s6, s10, 0x10da8100
	s_addc_u32 s7, s11, 0
	v_writelane_b32 v237, s6, 16
	s_mov_b32 s2, 0xb000
	v_mov_b32_e32 v0, s3
	v_writelane_b32 v237, s7, 17
	v_readlane_b32 s3, v238, 49
	v_readlane_b32 s6, v237, 4
	s_lshl_b32 s24, s6, 3
	v_mad_i32_i24 v118, v116, s2, v0
	v_mov_b32_e32 v0, s3
	v_readlane_b32 s3, v238, 50
	s_add_u32 s28, s10, 0xeda8100
	v_mad_i32_i24 v119, v116, s2, v0
	v_mov_b32_e32 v0, s3
	v_mad_i32_i24 v117, v116, s2, 0
	s_addc_u32 s29, s11, 0
	s_waitcnt vmcnt(8)
	v_mad_i32_i24 v120, v116, s2, v0
	v_readlane_b32 s2, v238, 40
	s_add_u32 s34, s2, s4
	v_readlane_b32 s2, v238, 41
	s_addc_u32 s35, s2, s5
	v_readlane_b32 s2, v238, 42
	v_readlane_b32 s7, v237, 5
	s_nop 0
	v_add_u16_e32 v121, s2, v116
	s_branch .LBB0_1501
	.p2align	6

; DI f32x16 mfma32(bf16x8 a, bf16x8 b, f32x16 c) { return __builtin_amdgcn_mfma_f32_32x32x16_bf16(a, b, c, 0, 0, 0); }
; DI void attn_na_unit(const Params& p, int li, int b, int r, int hp, char* smem) {
;     ...
;     if (kt + 1 < 8) {
;       const int k0 = (kt + 1) * 64;
; #pragma unroll
;       for (int i = 0; i < 4; ++i) { rk[i] = *(const u32x4*)(gk + (size_t)(k0 + i * 16) * 512); rv[i] = *(const u32x4*)(gv + (size_t)(k0 + i * 16) * 512); }
;     }
;     f32x16 s0, s1;
; #pragma unroll
;     for (int i = 0; i < 16; ++i) { s0[i] = -m; s1[i] = -m; }
;     {
;       bf16x8 kf[8];
; #pragma unroll
;       for (int s = 0; s < 4; ++s) {
;         kf[2 * s] = *(const bf16x8*)(ks + r32 * KR + (hs * 64 + s * 16 + hh * 8) * 2);
;         kf[2 * s + 1] = *(const bf16x8*)(ks + (32 + r32) * KR + (hs * 64 + s * 16 + hh * 8) * 2);
;       }
;       __builtin_amdgcn_sched_barrier(0); __builtin_amdgcn_s_setprio(1);
; #pragma unroll
;       for (int s = 0; s < 4; ++s) { s0 = mfma32(kf[2 * s], qf[s], s0); s1 = mfma32(kf[2 * s + 1], qf[s], s1); }
;     __builtin_amdgcn_s_setprio(0);
; }
;     const int drow = rs + kt - r + 7;
;     const float* trow = tab + hs * 465 + drow * 31;
; #pragma unroll
;     for (int i = 0; i < 16; ++i) {
;       const int kc0 = (i & 3) + 8 * (i >> 2) + 4 * hh;
;       const int kc1 = kc0 + 32;
;       const bool v0 = (unsigned)(kc0 - cs) < 16u;
;       const bool v1 = (unsigned)(kc1 - cs) < 16u;
;       const int d0 = v0 ? (kc0 - wq + 15) : 0;
;       const int d1 = v1 ? (kc1 - wq + 15) : 0;
;       const float b0 = trow[d0], b1 = trow[d1];
;       s0[i] = v0 ? s0[i] + b0 : -1e30f;
;       s1[i] = v1 ? s1[i] + b1 : -1e30f;
;     }
;     float alpha; bf16x8 pf[4];
.LBB0_1537:
	v_lshlrev_b32_e32 v126, 6, v39
	v_mul_u32_u24_e32 v39, 0x110, v33
	v_mul_u32_u24_e32 v42, 0x140, v33
	v_add_f32_e32 v33, 0, v50
	v_add_f32_e32 v50, 0, v60
	v_mul_f32_e32 v34, v50, v34
	v_add_f32_e32 v60, v33, v61
	v_cndmask_b32_e64 v128, v60, v33, s[6:7]
	v_xor_b32_e32 v220, 0x80000000, v128
	v_mov_b32_e32 v221, v220
	v_mov_b64_e32 v[222:223], v[220:221]
	v_mov_b64_e32 v[224:225], v[220:221]
	v_mov_b64_e32 v[226:227], v[220:221]
	v_mov_b64_e32 v[228:229], v[220:221]
	v_mov_b64_e32 v[230:231], v[220:221]
	v_mov_b64_e32 v[232:233], v[220:221]
	v_mov_b64_e32 v[234:235], v[220:221]
	v_cndmask_b32_e64 v127, v34, v50, s[6:7]
	s_movk_i32 s6, 0x7c
	v_mad_u32_u24 v34, v38, s6, v41
	v_add_u32_e32 v32, v34, v32
	v_lshlrev_b32_e32 v37, 2, v37
	v_mul_lo_u32 v36, v36, s6
	v_sub_u32_e32 v32, v32, v37
	v_lshlrev_b32_e32 v37, 1, v35
	v_sub_u32_e32 v32, v32, v36
	v_and_b32_e32 v37, 0x80, v37
	v_sub_u32_e32 v32, v32, v37
	v_add_u32_e32 v130, v120, v32
	v_and_b32_e32 v32, 15, v35
	v_and_b32_e32 v33, 3, v121
	v_lshlrev_b32_e32 v32, 4, v32
	v_lshlrev_b64 v[62:63], 9, v[144:145]
	v_lshl_add_u32 v38, v43, 2, v34
	v_lshl_or_b32 v144, v33, 8, v32
	v_sub_u32_e32 v38, v38, v36
	v_lshl_add_u64 v[32:33], v[62:63], 1, v[144:145]
	v_add_u32_e32 v129, v119, v38
	v_lshl_add_u64 v[114:115], s[34:35], 0, v[32:33]
	s_nop 7
	v_readfirstlane_b32 s6, v114
	s_nop 7
	v_subrev_u32_e32 v246, s6, v114
	v_add_u32_e32 v247, 0x4000, v246
	v_add_u32_e32 v248, 0x8000, v246
	v_add_u32_e32 v249, 0xc000, v246
	s_movk_i32 s9, 0xfc9c
	v_add_u32_e32 v144, v40, v39
	v_add_u32_e32 v148, v40, v42
	v_readfirstlane_b32 s100, v182
	s_branch .LBB0_1539
	.p2align	6

; template <class Epi, class Sched>
; DI void gemm_phase(LAS unsigned char* lds, const Gemm g, const Sched& S, const Epi& E) {
;     ...
;     const bool has_next = S.next(ui + 1, nxt);
;     const char* nA = has_next ? (const char*)g.A + (size_t)nxt.pm * tstep : cA; const char* nB = has_next ? (const char*)g.Bt + (size_t)nxt.pn * tstep : cB;
; #pragma unroll 1
;     for (int t = 0; t < nt; t += 2) {
;       const bool last = (t == nt - 2);
;       const char* a1 = cA + (size_t)(t + 1) * kstep;
;       const char* a2 = last ? nA : cA + (size_t)(t + 2) * kstep; const char* b2 = last ? nB : cB + (size_t)(t + 2) * kstep;
;       const char* a3 = a2 + kstep; const char* b3 = b2 + kstep;
;     ...
; #pragma unroll
;     for (int a = 0; a < 2; ++a)
; #pragma unroll
;       for (int b = 0; b < 2; ++b)
; #pragma unroll
;         for (int m = 0; m < 4; ++m)
; #pragma unroll
;           for (int n = 0; n < 2; ++n) acc[a][b][m][n] = (f32x4){0.f, 0.f, 0.f, 0.f};
.LBB0_1643:
	v_mov_b64_e32 v[0:1], s[30:31]
	s_ashr_i32 s19, s18, 31
	v_cmp_lt_i64_e32 vcc, s[20:21], v[0:1]
	s_lshl_b64 s[20:21], s[18:19], 19
	s_add_u32 s20, s36, s20
	s_addc_u32 s21, s37, s21
	s_and_b64 s[22:23], vcc, exec
	s_cselect_b32 s19, s21, s3
	s_cselect_b32 s35, s20, s2
	s_ashr_i32 s17, s16, 31
	s_lshl_b64 s[22:23], s[16:17], 19
	s_add_u32 s22, s38, s22
	s_addc_u32 s23, s39, s23
	s_and_b64 s[28:29], vcc, exec
	s_cselect_b32 s17, s23, s5
	s_cselect_b32 s51, s22, s4
	s_add_u32 s2, s2, 0x40080
	s_addc_u32 s3, s3, 0
	s_add_u32 s52, s4, 0x100
	v_mov_b32_e32 v0, 0
	s_addc_u32 s53, s5, 0
	s_mov_b32 s54, -2
	v_mov_b32_e32 v1, v0
	v_mov_b64_e32 v[2:3], v[0:1]
	v_mov_b64_e32 v[4:5], v[0:1]
	v_mov_b64_e32 v[6:7], v[0:1]
	v_mov_b64_e32 v[8:9], v[0:1]
	v_mov_b64_e32 v[10:11], v[0:1]
	v_mov_b64_e32 v[12:13], v[0:1]
	v_mov_b64_e32 v[14:15], v[0:1]
	v_mov_b64_e32 v[16:17], v[0:1]
	v_mov_b64_e32 v[18:19], v[0:1]
	v_mov_b64_e32 v[20:21], v[0:1]
	v_mov_b64_e32 v[22:23], v[0:1]
	v_mov_b64_e32 v[24:25], v[0:1]
	v_mov_b64_e32 v[26:27], v[0:1]
	v_mov_b64_e32 v[28:29], v[0:1]
	v_mov_b64_e32 v[30:31], v[0:1]
	v_mov_b64_e32 v[32:33], v[0:1]
	v_mov_b64_e32 v[34:35], v[0:1]
	v_mov_b64_e32 v[36:37], v[0:1]
	v_mov_b64_e32 v[38:39], v[0:1]
	v_mov_b64_e32 v[40:41], v[0:1]
	v_mov_b64_e32 v[42:43], v[0:1]
	v_mov_b64_e32 v[44:45], v[0:1]
	v_mov_b64_e32 v[46:47], v[0:1]
	v_mov_b64_e32 v[48:49], v[0:1]
	v_mov_b64_e32 v[50:51], v[0:1]
	v_mov_b64_e32 v[52:53], v[0:1]
	v_mov_b64_e32 v[54:55], v[0:1]
	v_mov_b64_e32 v[56:57], v[0:1]
	v_mov_b64_e32 v[58:59], v[0:1]
	v_mov_b64_e32 v[60:61], v[0:1]
	v_mov_b64_e32 v[62:63], v[0:1]
	v_mov_b64_e32 v[64:65], v[0:1]
	v_mov_b64_e32 v[66:67], v[0:1]
	v_mov_b64_e32 v[68:69], v[0:1]
	v_mov_b64_e32 v[70:71], v[0:1]
	v_mov_b64_e32 v[72:73], v[0:1]
	v_mov_b64_e32 v[74:75], v[0:1]
	v_mov_b64_e32 v[76:77], v[0:1]
	v_mov_b64_e32 v[78:79], v[0:1]
	v_mov_b64_e32 v[80:81], v[0:1]
	v_mov_b64_e32 v[82:83], v[0:1]
	v_mov_b64_e32 v[84:85], v[0:1]
	v_mov_b64_e32 v[86:87], v[0:1]
	v_mov_b64_e32 v[88:89], v[0:1]
	v_mov_b64_e32 v[90:91], v[0:1]
	v_mov_b64_e32 v[92:93], v[0:1]
	v_mov_b64_e32 v[94:95], v[0:1]
	v_mov_b64_e32 v[96:97], v[0:1]
	v_mov_b64_e32 v[98:99], v[0:1]
	v_mov_b64_e32 v[100:101], v[0:1]
	v_mov_b64_e32 v[102:103], v[0:1]
	v_mov_b64_e32 v[104:105], v[0:1]
	v_mov_b64_e32 v[106:107], v[0:1]
	v_mov_b64_e32 v[108:109], v[0:1]
	v_mov_b64_e32 v[110:111], v[0:1]
	v_mov_b64_e32 v[112:113], v[0:1]
	v_mov_b64_e32 v[114:115], v[0:1]
	v_mov_b64_e32 v[116:117], v[0:1]
	v_mov_b64_e32 v[118:119], v[0:1]
	v_mov_b64_e32 v[120:121], v[0:1]
	v_mov_b64_e32 v[122:123], v[0:1]
	v_mov_b64_e32 v[124:125], v[0:1]
	v_mov_b64_e32 v[126:127], v[0:1]
	v_add_u32_e32 v224, 0x10000, v158
	v_add_u32_e32 v225, 0x14000, v158
	v_add_u32_e32 v226, 0x18000, v158
	v_add_u32_e32 v227, 0x1c000, v158
	.p2align	6

; template <class Epi, class Sched>
; DI void gemm_phase(LAS unsigned char* lds, const Gemm g, const Sched& S, const Epi& E) {
;     ...
;     const bool has_next = S.next(ui + 1, nxt);
;     const char* nA = has_next ? (const char*)g.A + (size_t)nxt.pm * tstep : cA; const char* nB = has_next ? (const char*)g.Bt + (size_t)nxt.pn * tstep : cB;
; #pragma unroll 1
;     for (int t = 0; t < nt; t += 2) {
;       const bool last = (t == nt - 2);
;       const char* a1 = cA + (size_t)(t + 1) * kstep;
;       const char* a2 = last ? nA : cA + (size_t)(t + 2) * kstep; const char* b2 = last ? nB : cB + (size_t)(t + 2) * kstep;
;       const char* a3 = a2 + kstep; const char* b3 = b2 + kstep;
;     ...
; #pragma unroll
;     for (int a = 0; a < 2; ++a)
; #pragma unroll
;       for (int b = 0; b < 2; ++b)
; #pragma unroll
;         for (int m = 0; m < 4; ++m)
; #pragma unroll
;           for (int n = 0; n < 2; ++n) acc[a][b][m][n] = (f32x4){0.f, 0.f, 0.f, 0.f};
.LBB0_1828:
	v_readlane_b32 s12, v238, 61
	v_readlane_b32 s13, v238, 62
	s_ashr_i32 s7, s6, 31
	s_mov_b32 s50, -2
	v_mov_b64_e32 v[0:1], s[12:13]
	v_cmp_lt_i64_e32 vcc, s[10:11], v[0:1]
	s_lshl_b64 s[10:11], s[6:7], 19
	s_add_u32 s10, s21, s10
	s_addc_u32 s11, s22, s11
	s_and_b64 s[12:13], vcc, exec
	s_cselect_b32 s7, s11, s15
	s_cselect_b32 s46, s10, s14
	s_ashr_i32 s5, s4, 31
	s_lshl_b64 s[12:13], s[4:5], 19
	s_add_u32 s12, s23, s12
	s_addc_u32 s13, s28, s13
	s_and_b64 s[18:19], vcc, exec
	s_cselect_b32 s5, s13, s17
	s_cselect_b32 s47, s12, s16
	s_add_u32 s14, s14, 0x40080
	s_addc_u32 s15, s15, 0
	s_add_u32 s48, s16, 0x100
	v_mov_b32_e32 v0, 0
	s_addc_u32 s49, s17, 0
	v_mov_b32_e32 v1, v0
	v_mov_b64_e32 v[2:3], v[0:1]
	v_mov_b64_e32 v[4:5], v[0:1]
	v_mov_b64_e32 v[6:7], v[0:1]
	v_mov_b64_e32 v[8:9], v[0:1]
	v_mov_b64_e32 v[10:11], v[0:1]
	v_mov_b64_e32 v[12:13], v[0:1]
	v_mov_b64_e32 v[14:15], v[0:1]
	v_mov_b64_e32 v[16:17], v[0:1]
	v_mov_b64_e32 v[18:19], v[0:1]
	v_mov_b64_e32 v[20:21], v[0:1]
	v_mov_b64_e32 v[22:23], v[0:1]
	v_mov_b64_e32 v[24:25], v[0:1]
	v_mov_b64_e32 v[26:27], v[0:1]
	v_mov_b64_e32 v[28:29], v[0:1]
	v_mov_b64_e32 v[30:31], v[0:1]
	v_mov_b64_e32 v[32:33], v[0:1]
	v_mov_b64_e32 v[34:35], v[0:1]
	v_mov_b64_e32 v[36:37], v[0:1]
	v_mov_b64_e32 v[38:39], v[0:1]
	v_mov_b64_e32 v[40:41], v[0:1]
	v_mov_b64_e32 v[42:43], v[0:1]
	v_mov_b64_e32 v[44:45], v[0:1]
	v_mov_b64_e32 v[46:47], v[0:1]
	v_mov_b64_e32 v[48:49], v[0:1]
	v_mov_b64_e32 v[50:51], v[0:1]
	v_mov_b64_e32 v[52:53], v[0:1]
	v_mov_b64_e32 v[54:55], v[0:1]
	v_mov_b64_e32 v[56:57], v[0:1]
	v_mov_b64_e32 v[58:59], v[0:1]
	v_mov_b64_e32 v[60:61], v[0:1]
	v_mov_b64_e32 v[62:63], v[0:1]
	v_mov_b64_e32 v[64:65], v[0:1]
	v_mov_b64_e32 v[66:67], v[0:1]
	v_mov_b64_e32 v[68:69], v[0:1]
	v_mov_b64_e32 v[70:71], v[0:1]
	v_mov_b64_e32 v[72:73], v[0:1]
	v_mov_b64_e32 v[74:75], v[0:1]
	v_mov_b64_e32 v[76:77], v[0:1]
	v_mov_b64_e32 v[78:79], v[0:1]
	v_mov_b64_e32 v[80:81], v[0:1]
	v_mov_b64_e32 v[82:83], v[0:1]
	v_mov_b64_e32 v[84:85], v[0:1]
	v_mov_b64_e32 v[86:87], v[0:1]
	v_mov_b64_e32 v[88:89], v[0:1]
	v_mov_b64_e32 v[90:91], v[0:1]
	v_mov_b64_e32 v[92:93], v[0:1]
	v_mov_b64_e32 v[94:95], v[0:1]
	v_mov_b64_e32 v[96:97], v[0:1]
	v_mov_b64_e32 v[98:99], v[0:1]
	v_mov_b64_e32 v[100:101], v[0:1]
	v_mov_b64_e32 v[102:103], v[0:1]
	v_mov_b64_e32 v[104:105], v[0:1]
	v_mov_b64_e32 v[106:107], v[0:1]
	v_mov_b64_e32 v[108:109], v[0:1]
	v_mov_b64_e32 v[110:111], v[0:1]
	v_mov_b64_e32 v[112:113], v[0:1]
	v_mov_b64_e32 v[114:115], v[0:1]
	v_mov_b64_e32 v[116:117], v[0:1]
	v_mov_b64_e32 v[118:119], v[0:1]
	v_mov_b64_e32 v[120:121], v[0:1]
	v_mov_b64_e32 v[122:123], v[0:1]
	v_mov_b64_e32 v[124:125], v[0:1]
	v_mov_b64_e32 v[126:127], v[0:1]
	v_add_u32_e32 v224, 0x10000, v142
	v_add_u32_e32 v225, 0x14000, v142
	v_add_u32_e32 v226, 0x18000, v142
	v_add_u32_e32 v227, 0x1c000, v142
	.p2align	6

; template <class Epi, class Sched>
; DI void gemm_phase(LAS unsigned char* lds, const Gemm g, const Sched& S, const Epi& E) {
;     ...
;     const bool has_next = S.next(ui + 1, nxt);
;     const char* nA = has_next ? (const char*)g.A + (size_t)nxt.pm * tstep : cA; const char* nB = has_next ? (const char*)g.Bt + (size_t)nxt.pn * tstep : cB;
; #pragma unroll 1
;     for (int t = 0; t < nt; t += 2) {
;       const bool last = (t == nt - 2);
;       const char* a1 = cA + (size_t)(t + 1) * kstep;
;       const char* a2 = last ? nA : cA + (size_t)(t + 2) * kstep; const char* b2 = last ? nB : cB + (size_t)(t + 2) * kstep;
;       const char* a3 = a2 + kstep; const char* b3 = b2 + kstep;
;     ...
; #pragma unroll
;     for (int a = 0; a < 2; ++a)
; #pragma unroll
;       for (int b = 0; b < 2; ++b)
; #pragma unroll
;         for (int m = 0; m < 4; ++m)
; #pragma unroll
;           for (int n = 0; n < 2; ++n) acc[a][b][m][n] = (f32x4){0.f, 0.f, 0.f, 0.f};
.LBB0_1904:
	v_mov_b64_e32 v[0:1], s[30:31]
	s_ashr_i32 s11, s10, 31
	v_cmp_lt_i64_e32 vcc, s[12:13], v[0:1]
	s_lshl_b64 s[12:13], s[10:11], 21
	s_add_u32 s12, s34, s12
	s_addc_u32 s13, s35, s13
	s_and_b64 s[14:15], vcc, exec
	s_cselect_b32 s11, s13, s21
	s_cselect_b32 s17, s12, s20
	s_ashr_i32 s7, s6, 31
	s_lshl_b64 s[14:15], s[6:7], 21
	s_add_u32 s14, s36, s14
	s_addc_u32 s15, s37, s15
	s_and_b64 s[28:29], vcc, exec
	s_cselect_b32 s7, s15, s23
	s_cselect_b32 s19, s14, s22
	s_add_u32 s20, s20, 0x100080
	s_addc_u32 s21, s21, 0
	s_add_u32 s24, s22, 0x100
	v_mov_b32_e32 v0, 0
	s_addc_u32 s49, s23, 0
	s_mov_b32 s50, -2
	v_mov_b32_e32 v1, v0
	v_mov_b64_e32 v[2:3], v[0:1]
	v_mov_b64_e32 v[4:5], v[0:1]
	v_mov_b64_e32 v[6:7], v[0:1]
	v_mov_b64_e32 v[8:9], v[0:1]
	v_mov_b64_e32 v[10:11], v[0:1]
	v_mov_b64_e32 v[12:13], v[0:1]
	v_mov_b64_e32 v[14:15], v[0:1]
	v_mov_b64_e32 v[16:17], v[0:1]
	v_mov_b64_e32 v[18:19], v[0:1]
	v_mov_b64_e32 v[20:21], v[0:1]
	v_mov_b64_e32 v[22:23], v[0:1]
	v_mov_b64_e32 v[24:25], v[0:1]
	v_mov_b64_e32 v[26:27], v[0:1]
	v_mov_b64_e32 v[28:29], v[0:1]
	v_mov_b64_e32 v[30:31], v[0:1]
	v_mov_b64_e32 v[32:33], v[0:1]
	v_mov_b64_e32 v[34:35], v[0:1]
	v_mov_b64_e32 v[36:37], v[0:1]
	v_mov_b64_e32 v[38:39], v[0:1]
	v_mov_b64_e32 v[40:41], v[0:1]
	v_mov_b64_e32 v[42:43], v[0:1]
	v_mov_b64_e32 v[44:45], v[0:1]
	v_mov_b64_e32 v[46:47], v[0:1]
	v_mov_b64_e32 v[48:49], v[0:1]
	v_mov_b64_e32 v[50:51], v[0:1]
	v_mov_b64_e32 v[52:53], v[0:1]
	v_mov_b64_e32 v[54:55], v[0:1]
	v_mov_b64_e32 v[56:57], v[0:1]
	v_mov_b64_e32 v[58:59], v[0:1]
	v_mov_b64_e32 v[60:61], v[0:1]
	v_mov_b64_e32 v[62:63], v[0:1]
	v_mov_b64_e32 v[64:65], v[0:1]
	v_mov_b64_e32 v[66:67], v[0:1]
	v_mov_b64_e32 v[68:69], v[0:1]
	v_mov_b64_e32 v[70:71], v[0:1]
	v_mov_b64_e32 v[72:73], v[0:1]
	v_mov_b64_e32 v[74:75], v[0:1]
	v_mov_b64_e32 v[76:77], v[0:1]
	v_mov_b64_e32 v[78:79], v[0:1]
	v_mov_b64_e32 v[80:81], v[0:1]
	v_mov_b64_e32 v[82:83], v[0:1]
	v_mov_b64_e32 v[84:85], v[0:1]
	v_mov_b64_e32 v[86:87], v[0:1]
	v_mov_b64_e32 v[88:89], v[0:1]
	v_mov_b64_e32 v[90:91], v[0:1]
	v_mov_b64_e32 v[92:93], v[0:1]
	v_mov_b64_e32 v[94:95], v[0:1]
	v_mov_b64_e32 v[96:97], v[0:1]
	v_mov_b64_e32 v[98:99], v[0:1]
	v_mov_b64_e32 v[100:101], v[0:1]
	v_mov_b64_e32 v[102:103], v[0:1]
	v_mov_b64_e32 v[104:105], v[0:1]
	v_mov_b64_e32 v[106:107], v[0:1]
	v_mov_b64_e32 v[108:109], v[0:1]
	v_mov_b64_e32 v[110:111], v[0:1]
	v_mov_b64_e32 v[112:113], v[0:1]
	v_mov_b64_e32 v[114:115], v[0:1]
	v_mov_b64_e32 v[116:117], v[0:1]
	v_mov_b64_e32 v[118:119], v[0:1]
	v_mov_b64_e32 v[120:121], v[0:1]
	v_mov_b64_e32 v[122:123], v[0:1]
	v_mov_b64_e32 v[124:125], v[0:1]
	v_mov_b64_e32 v[126:127], v[0:1]
	v_add_u32_e32 v224, 0x10000, v146
	v_add_u32_e32 v225, 0x14000, v146
	v_add_u32_e32 v226, 0x18000, v146
	v_add_u32_e32 v227, 0x1c000, v146
	.p2align	6
